# DK32 attention: max subtraction of both streams folded into the QK MFMA C operands; register plan repacked
# speedup vs baseline: 1.0305x; 1.0049x over previous
; template <int DK>
; DI void attn_item(const Params& p, int layer, int b, int hd, int qt, int ctxq, char* smem) {
;     ...
;     for (int kt = 0; kt < nkt; ++kt) {
;         const int cur = kt & 1;
;         const bf16_t* kb_ = sK + cur * 64 * 72; const bf16_t* vb_ = sV + cur * 64 * 68;
; #pragma unroll
;         for (int s = 0; s < 2; ++s) {
;             if (s == 1) {
;                 if (kt + 1 < nkt) {
; #pragma unroll
;                     for (int i = 0; i < 2; ++i) { rk[i] = *(const u32x4*)(Kg + (size_t)((kt + 1) * 64 + srow + 32 * i) * 64 + sc8); rv[i] = *(const u32x4*)(Vg + (size_t)(srow + 32 * i) * NKEY + (kt + 1) * 64 + sc8); }
;                 }
;             }
;             f32x16 x[2];
; #pragma unroll
;             for (int kb = 0; kb < 2; ++kb)
; #pragma unroll
;                 for (int i = 0; i < 16; ++i) x[kb][i] = 0.f;
;             const int kofs = DK == 32 ? 32 * s : 0;
; #pragma unroll
;             for (int ks = 0; ks < NKS; ++ks) {
;                 const bf16x8 a0 = *(const bf16x8*)(kb_ + r * 72 + kofs + 16 * ks + 8 * h), a1 = *(const bf16x8*)(kb_ + (32 + r) * 72 + kofs + 16 * ks + 8 * h);
;                 const bf16x8 qv = *(const bf16x8*)(sQ + ((s * NKS + ks) * 64 + lane) * 8);
;                 x[0] = MFMA32(a0, qv, x[0]); x[1] = MFMA32(a1, qv, x[1]);
;             }
;             float mx = x[0][0];
; #pragma unroll
;             for (int i = 1; i < 16; ++i) mx = fmaxf(mx, x[0][i]);
; #pragma unroll
;             for (int i = 0; i < 16; ++i) mx = fmaxf(mx, x[1][i]);
;             mx = fmaxf(mx, shx(mx, lane, 32));
;             if (__builtin_amdgcn_ballot_w64(mx > m_[s] + 8.f) != 0) {
;                 const float mn = fmaxf(m_[s], mx);
;                 const float al = __builtin_amdgcn_exp2f(m_[s] - mn);
;                 m_[s] = mn;
;                 l_[s] *= al;
; #pragma unroll
;                 for (int d = 0; d < 2; ++d)
; #pragma unroll
;                     for (int i = 0; i < 16; ++i) O[s][d][i] *= al;
;             }
;             const f32x2 mref = {m_[s], m_[s]};
;             float ps = 0.f;
; #pragma unroll
;             for (int kb = 0; kb < 2; ++kb)
; #pragma unroll
;                 for (int i2 = 0; i2 < 8; ++i2) {
;                     f32x2 t = {x[kb][2 * i2], x[kb][2 * i2 + 1]};
;                     asm("v_pk_add_f32 %0, %1, %2 neg_lo:[0,1] neg_hi:[0,1]" : "=v"(t) : "v"(t), "v"(mref));
.LBB0_158:
	s_mov_b32 s8, 0
	ds_read_b128 v[222:225], v171 offset:35840
	ds_read_b128 v[240:243], v171 offset:36864
	ds_read_b128 v[244:247], v171 offset:37888
	ds_read_b128 v[248:251], v171 offset:38912
	ds_read_b128 v[128:131], v149
	ds_read_b128 v[132:135], v149 offset:4608
	ds_read_b128 v[136:139], v149 offset:32
	ds_read_b128 v[140:143], v149 offset:4640
	v_lshl_add_u64 v[226:227], v[154:155], 0, v[160:161]
	s_mov_b64 s[10:11], 0x84000
	v_lshl_add_u64 v[236:237], v[226:227], 0, s[10:11]
	v_lshl_add_u64 v[230:231], v[156:157], 0, v[160:161]
	s_mov_b64 s[10:11], 0x3000
	v_lshl_add_u64 v[230:231], v[230:231], 0, s[10:11]
	global_load_dwordx4 v[206:209], v[230:231], off offset:-4096
	global_load_dwordx4 v[210:213], v[230:231], off
	global_load_dwordx4 v[214:217], v[226:227], off offset:128
	global_load_dwordx4 v[218:221], v[236:237], off offset:128
	v_mov_b32_e32 v153, v152
	v_mov_b32_e32 v147, v146
	s_and_b32 s9, s8, 1
	s_mul_i32 s10, s9, 0x2400
	s_mul_i32 s11, s9, 0x2200
	v_add_u32_e32 v173, s10, v149
	v_add_u32_e32 v236, s11, v172
	v_add_u32_e32 v237, 0x5800, v236
	v_add_u32_e32 v236, 0x4800, v236
	s_waitcnt lgkmcnt(0)
	v_mfma_f32_32x32x16_bf16 v[80:95], v[128:131], v[222:225], 0
	v_mfma_f32_32x32x16_bf16 v[80:95], v[136:139], v[240:243], v[80:95]
	v_mfma_f32_32x32x16_bf16 v[64:79], v[132:135], v[222:225], 0
	v_mfma_f32_32x32x16_bf16 v[64:79], v[140:143], v[240:243], v[64:79]
	ds_read2_b64 v[96:99], v236 offset0:0 offset1:2
	ds_read2_b64 v[112:115], v237 offset0:32 offset1:34
	ds_read2_b64 v[100:103], v236 offset0:4 offset1:6
	ds_read2_b64 v[116:119], v237 offset0:36 offset1:38
	ds_read2_b64 v[104:107], v236 offset0:8 offset1:10
	ds_read2_b64 v[120:123], v237 offset0:40 offset1:42
	ds_read2_b64 v[108:111], v236 offset0:12 offset1:14
	ds_read2_b64 v[124:127], v237 offset0:44 offset1:46
	ds_read_b128 v[128:131], v173 offset:64
	ds_read_b128 v[132:135], v173 offset:4672
	ds_read_b128 v[136:139], v173 offset:96
	ds_read_b128 v[140:143], v173 offset:4704
	v_max3_f32 v233, v80, v81, v82
	v_max3_f32 v233, v233, v83, v84
	v_max3_f32 v233, v233, v85, v86
	v_max3_f32 v233, v233, v87, v88
	v_max3_f32 v233, v233, v89, v90
	v_max3_f32 v233, v233, v91, v92
	v_max3_f32 v233, v233, v93, v94
	v_max3_f32 v233, v233, v95, v64
	v_max3_f32 v233, v233, v65, v66
	v_max3_f32 v233, v233, v67, v68
	v_max3_f32 v233, v233, v69, v70
	v_max3_f32 v233, v233, v71, v72
	v_max3_f32 v233, v233, v73, v74
	v_max3_f32 v233, v233, v75, v76
	v_max3_f32 v233, v233, v77, v78
	v_max_f32_e32 v233, v233, v79
	v_mov_b32_e32 v234, v233
	s_nop 1
	v_permlane32_swap_b32_e32 v234, v233
	s_nop 0
	v_max_f32_e32 v233, v233, v234
	v_add_f32_e32 v234, 0x41000000, v152
	v_cmp_gt_f32_e32 vcc, v233, v234
	s_cbranch_vccz .Lat32_nors0f
	v_max_f32_e32 v239, v152, v233
	v_sub_f32_e32 v234, v152, v239
	v_exp_f32_e32 v234, v234
	v_mov_b32_e32 v152, v239
	v_mov_b32_e32 v153, v239
	v_mul_f32_e32 v151, v151, v234
	v_mul_f32_e32 v32, v32, v234
	v_mul_f32_e32 v33, v33, v234
	v_mul_f32_e32 v34, v34, v234
	v_mul_f32_e32 v35, v35, v234
	v_mul_f32_e32 v36, v36, v234
	v_mul_f32_e32 v37, v37, v234
	v_mul_f32_e32 v38, v38, v234
	v_mul_f32_e32 v39, v39, v234
	v_mul_f32_e32 v40, v40, v234
	v_mul_f32_e32 v41, v41, v234
	v_mul_f32_e32 v42, v42, v234
	v_mul_f32_e32 v43, v43, v234
	v_mul_f32_e32 v44, v44, v234
	v_mul_f32_e32 v45, v45, v234
	v_mul_f32_e32 v46, v46, v234
	v_mul_f32_e32 v47, v47, v234
	v_mul_f32_e32 v0, v0, v234
	v_mul_f32_e32 v1, v1, v234
	v_mul_f32_e32 v2, v2, v234
	v_mul_f32_e32 v3, v3, v234
	v_mul_f32_e32 v4, v4, v234
	v_mul_f32_e32 v5, v5, v234
	v_mul_f32_e32 v6, v6, v234
	v_mul_f32_e32 v7, v7, v234
	v_mul_f32_e32 v8, v8, v234
	v_mul_f32_e32 v9, v9, v234
	v_mul_f32_e32 v10, v10, v234
	v_mul_f32_e32 v11, v11, v234
	v_mul_f32_e32 v12, v12, v234
	v_mul_f32_e32 v13, v13, v234
	v_mul_f32_e32 v14, v14, v234
	v_mul_f32_e32 v15, v15, v234
.Lat32_nors0f:
	v_pk_add_f32 v[80:81], v[80:81], v[152:153] neg_lo:[0,1] neg_hi:[0,1]
	v_pk_add_f32 v[82:83], v[82:83], v[152:153] neg_lo:[0,1] neg_hi:[0,1]
	v_pk_add_f32 v[84:85], v[84:85], v[152:153] neg_lo:[0,1] neg_hi:[0,1]
	v_pk_add_f32 v[86:87], v[86:87], v[152:153] neg_lo:[0,1] neg_hi:[0,1]
	v_exp_f32_e32 v80, v80
	v_exp_f32_e32 v81, v81
	v_exp_f32_e32 v82, v82
	v_exp_f32_e32 v83, v83
	v_exp_f32_e32 v84, v84
	v_exp_f32_e32 v85, v85
	v_exp_f32_e32 v86, v86
	v_exp_f32_e32 v87, v87
	v_add_f32_e32 v236, v80, v82
	v_add_f32_e32 v237, v81, v83
	v_add_f32_e32 v236, v236, v84
	v_add_f32_e32 v237, v237, v85
	v_add_f32_e32 v236, v236, v86
	v_add_f32_e32 v237, v237, v87
	v_cvt_pk_bf16_f32 v80, v80, v81
	v_cvt_pk_bf16_f32 v81, v82, v83
	v_cvt_pk_bf16_f32 v82, v84, v85
	v_cvt_pk_bf16_f32 v83, v86, v87
	s_waitcnt lgkmcnt(0)
; template <int DK>
; DI void attn_item(const Params& p, int layer, int b, int hd, int qt, int ctxq, char* smem) {
;     ...
;             float mx = x[0][0];
; #pragma unroll
;             for (int i = 1; i < 16; ++i) mx = fmaxf(mx, x[0][i]);
; #pragma unroll
;             for (int i = 0; i < 16; ++i) mx = fmaxf(mx, x[1][i]);
;             mx = fmaxf(mx, shx(mx, lane, 32));
;             if (__builtin_amdgcn_ballot_w64(mx > m_[s] + 8.f) != 0) {
;                 const float mn = fmaxf(m_[s], mx);
;                 const float al = __builtin_amdgcn_exp2f(m_[s] - mn);
;                 m_[s] = mn;
;                 l_[s] *= al;
; #pragma unroll
;                 for (int d = 0; d < 2; ++d)
; #pragma unroll
;                     for (int i = 0; i < 16; ++i) O[s][d][i] *= al;
;             }
;             const f32x2 mref = {m_[s], m_[s]};
;             float ps = 0.f;
; #pragma unroll
;             for (int kb = 0; kb < 2; ++kb)
; #pragma unroll
;                 for (int i2 = 0; i2 < 8; ++i2) {
;                     f32x2 t = {x[kb][2 * i2], x[kb][2 * i2 + 1]};
;                     asm("v_pk_add_f32 %0, %1, %2 neg_lo:[0,1] neg_hi:[0,1]" : "=v"(t) : "v"(t), "v"(mref));
;                     const float e0 = __builtin_amdgcn_exp2f(t.x), e1 = __builtin_amdgcn_exp2f(t.y);
;                     x[kb][2 * i2] = e0; x[kb][2 * i2 + 1] = e1; ps += e0 + e1;
;                 }
;             l_[s] += ps;
; #pragma unroll
;             for (int kb = 0; kb < 2; ++kb)
; #pragma unroll
;                 for (int st = 0; st < 2; ++st) {
;                     u32x4 w;
;                     w.x = pk_bf16(x[kb][8 * st], x[kb][8 * st + 1]); w.y = pk_bf16(x[kb][8 * st + 2], x[kb][8 * st + 3]);
;                     w.z = pk_bf16(x[kb][8 * st + 4], x[kb][8 * st + 5]); w.w = pk_bf16(x[kb][8 * st + 6], x[kb][8 * st + 7]);
;                     const bf16x8 pfr = __builtin_bit_cast(bf16x8, w);
; #pragma unroll
;                     for (int d = 0; d < 2; ++d) {
;                         const bf16_t* vp = vb_ + (32 * d + r) * 68 + 32 * kb + 16 * st + 4 * h;
;                         const s16x4 lo = *(const s16x4*)vp, hi = *(const s16x4*)(vp + 8);
;                         const bf16x8 vf = __builtin_shufflevector(lo, hi, 0, 1, 2, 3, 4, 5, 6, 7);
;                         O[s][d] = MFMA32(vf, pfr, O[s][d]);
;                     }
;                 }
;         }
;         if (kt + 1 < nkt) {
	v_pk_add_f32 v[88:89], v[88:89], v[152:153] neg_lo:[0,1] neg_hi:[0,1]
	v_pk_add_f32 v[90:91], v[90:91], v[152:153] neg_lo:[0,1] neg_hi:[0,1]
	v_pk_add_f32 v[92:93], v[92:93], v[152:153] neg_lo:[0,1] neg_hi:[0,1]
	v_pk_add_f32 v[94:95], v[94:95], v[152:153] neg_lo:[0,1] neg_hi:[0,1]
	v_mfma_f32_32x32x16_bf16 v[32:47], v[96:99], v[80:83], v[32:47]
	v_mfma_f32_32x32x16_bf16 v[0:15], v[112:115], v[80:83], v[0:15]
	v_exp_f32_e32 v88, v88
	v_exp_f32_e32 v89, v89
	v_exp_f32_e32 v90, v90
	v_exp_f32_e32 v91, v91
	v_exp_f32_e32 v92, v92
	v_exp_f32_e32 v93, v93
	v_exp_f32_e32 v94, v94
	v_exp_f32_e32 v95, v95
	v_add_f32_e32 v236, v236, v88
	v_add_f32_e32 v237, v237, v89
	v_add_f32_e32 v236, v236, v90
	v_add_f32_e32 v237, v237, v91
	v_add_f32_e32 v236, v236, v92
	v_add_f32_e32 v237, v237, v93
	v_add_f32_e32 v236, v236, v94
	v_add_f32_e32 v237, v237, v95
	v_cvt_pk_bf16_f32 v88, v88, v89
	v_cvt_pk_bf16_f32 v89, v90, v91
	v_cvt_pk_bf16_f32 v90, v92, v93
	v_cvt_pk_bf16_f32 v91, v94, v95
	v_pk_add_f32 v[64:65], v[64:65], v[152:153] neg_lo:[0,1] neg_hi:[0,1]
	v_pk_add_f32 v[66:67], v[66:67], v[152:153] neg_lo:[0,1] neg_hi:[0,1]
	v_pk_add_f32 v[68:69], v[68:69], v[152:153] neg_lo:[0,1] neg_hi:[0,1]
	v_pk_add_f32 v[70:71], v[70:71], v[152:153] neg_lo:[0,1] neg_hi:[0,1]
	v_mfma_f32_32x32x16_bf16 v[32:47], v[100:103], v[88:91], v[32:47]
	v_mfma_f32_32x32x16_bf16 v[0:15], v[116:119], v[88:91], v[0:15]
	v_mfma_f32_32x32x16_bf16 v[80:95], v[128:131], v[244:247], 0
	v_mfma_f32_32x32x16_bf16 v[80:95], v[136:139], v[248:251], v[80:95]
	v_exp_f32_e32 v64, v64
	v_exp_f32_e32 v65, v65
	v_exp_f32_e32 v66, v66
	v_exp_f32_e32 v67, v67
	v_exp_f32_e32 v68, v68
	v_exp_f32_e32 v69, v69
	v_exp_f32_e32 v70, v70
	v_exp_f32_e32 v71, v71
	v_add_f32_e32 v236, v236, v64
	v_add_f32_e32 v237, v237, v65
	v_add_f32_e32 v236, v236, v66
	v_add_f32_e32 v237, v237, v67
	v_add_f32_e32 v236, v236, v68
	v_add_f32_e32 v237, v237, v69
	v_add_f32_e32 v236, v236, v70
	v_add_f32_e32 v237, v237, v71
	v_cvt_pk_bf16_f32 v64, v64, v65
	v_cvt_pk_bf16_f32 v65, v66, v67
	v_cvt_pk_bf16_f32 v66, v68, v69
	v_cvt_pk_bf16_f32 v67, v70, v71
	v_pk_add_f32 v[72:73], v[72:73], v[152:153] neg_lo:[0,1] neg_hi:[0,1]
	v_pk_add_f32 v[74:75], v[74:75], v[152:153] neg_lo:[0,1] neg_hi:[0,1]
	v_pk_add_f32 v[76:77], v[76:77], v[152:153] neg_lo:[0,1] neg_hi:[0,1]
	v_pk_add_f32 v[78:79], v[78:79], v[152:153] neg_lo:[0,1] neg_hi:[0,1]
	v_mfma_f32_32x32x16_bf16 v[32:47], v[104:107], v[64:67], v[32:47]
	v_mfma_f32_32x32x16_bf16 v[0:15], v[120:123], v[64:67], v[0:15]
	v_exp_f32_e32 v72, v72
	v_exp_f32_e32 v73, v73
	v_exp_f32_e32 v74, v74
	v_exp_f32_e32 v75, v75
	v_exp_f32_e32 v76, v76
	v_exp_f32_e32 v77, v77
	v_exp_f32_e32 v78, v78
	v_exp_f32_e32 v79, v79
	v_add_f32_e32 v236, v236, v72
	v_add_f32_e32 v237, v237, v73
	v_add_f32_e32 v236, v236, v74
	v_add_f32_e32 v237, v237, v75
	v_add_f32_e32 v236, v236, v76
	v_add_f32_e32 v237, v237, v77
	v_add_f32_e32 v236, v236, v78
	v_add_f32_e32 v237, v237, v79
	v_cvt_pk_bf16_f32 v72, v72, v73
	v_cvt_pk_bf16_f32 v73, v74, v75
	v_cvt_pk_bf16_f32 v74, v76, v77
	v_cvt_pk_bf16_f32 v75, v78, v79
	v_add_f32_e32 v236, v236, v237
	v_add_f32_e32 v151, v151, v236
	v_mfma_f32_32x32x16_bf16 v[32:47], v[108:111], v[72:75], v[32:47]
	v_mfma_f32_32x32x16_bf16 v[0:15], v[124:127], v[72:75], v[0:15]
	v_mfma_f32_32x32x16_bf16 v[64:79], v[132:135], v[244:247], 0
	v_mfma_f32_32x32x16_bf16 v[64:79], v[140:143], v[248:251], v[64:79]
	v_sub_f32_e32 v174, 0, v152
	v_sub_f32_e32 v175, 0, v152
	v_sub_f32_e32 v176, 0, v152
	v_sub_f32_e32 v177, 0, v152
	v_sub_f32_e32 v178, 0, v152
	v_sub_f32_e32 v179, 0, v152
	v_sub_f32_e32 v180, 0, v152
	v_sub_f32_e32 v181, 0, v152
	v_sub_f32_e32 v182, 0, v152
	v_sub_f32_e32 v183, 0, v152
	v_sub_f32_e32 v184, 0, v152
	v_sub_f32_e32 v185, 0, v152
	v_sub_f32_e32 v186, 0, v152
	v_sub_f32_e32 v187, 0, v152
	v_sub_f32_e32 v188, 0, v152
	v_sub_f32_e32 v189, 0, v152
	s_xor_b32 s9, s9, 1
	s_mul_i32 s10, s9, 0x2400
	s_mul_i32 s11, s9, 0x2200
	v_add_u32_e32 v233, s10, v148
	v_add_u32_e32 v234, s11, v150
	v_add_u32_e32 v239, 0x5900, v234
	v_add_u32_e32 v234, 0x4800, v234
	v_add_u32_e32 v173, s10, v149
	s_waitcnt vmcnt(0)
	ds_write_b128 v233, v[206:209]
	ds_write_b128 v233, v[210:213] offset:4608
	ds_write2_b64 v234, v[214:215], v[216:217] offset1:1
	ds_write2_b64 v239, v[218:219], v[220:221] offset1:1
	s_mov_b64 s[10:11], 0x80
	v_lshl_add_u64 v[226:227], v[226:227], 0, s[10:11]
	s_mov_b64 s[10:11], 0x2000
	v_lshl_add_u64 v[230:231], v[230:231], 0, s[10:11]
	s_mov_b64 s[10:11], 0x84000
	v_lshl_add_u64 v[236:237], v[226:227], 0, s[10:11]
	global_load_dwordx4 v[206:209], v[230:231], off offset:-4096
	global_load_dwordx4 v[210:213], v[230:231], off
	global_load_dwordx4 v[214:217], v[226:227], off offset:128
	global_load_dwordx4 v[218:221], v[236:237], off offset:128
	v_max3_f32 v233, v80, v81, v82
	v_max3_f32 v233, v233, v83, v84
	v_max3_f32 v233, v233, v85, v86
	v_max3_f32 v233, v233, v87, v88
	v_max3_f32 v233, v233, v89, v90
	v_max3_f32 v233, v233, v91, v92
	v_max3_f32 v233, v233, v93, v94
	v_max3_f32 v233, v233, v95, v64
	v_max3_f32 v233, v233, v65, v66
	v_max3_f32 v233, v233, v67, v68
	v_max3_f32 v233, v233, v69, v70
	v_max3_f32 v233, v233, v71, v72
	v_max3_f32 v233, v233, v73, v74
	v_max3_f32 v233, v233, v75, v76
	v_max3_f32 v233, v233, v77, v78
	v_max_f32_e32 v233, v233, v79
	v_mov_b32_e32 v234, v233
	s_nop 1
	v_permlane32_swap_b32_e32 v234, v233
	s_nop 0
	v_max_f32_e32 v233, v233, v234
	v_add_f32_e32 v234, 0x41000000, v146
	v_cmp_gt_f32_e32 vcc, v233, v234
	s_cbranch_vccz .Lat32_nors1f
	v_max_f32_e32 v239, v146, v233
	v_sub_f32_e32 v234, v146, v239
	v_exp_f32_e32 v234, v234
	v_mov_b32_e32 v146, v239
	v_mov_b32_e32 v147, v239
	v_mul_f32_e32 v170, v170, v234
	v_mul_f32_e32 v48, v48, v234
	v_mul_f32_e32 v49, v49, v234
	v_mul_f32_e32 v50, v50, v234
	v_mul_f32_e32 v51, v51, v234
	v_mul_f32_e32 v52, v52, v234
	v_mul_f32_e32 v53, v53, v234
	v_mul_f32_e32 v54, v54, v234
	v_mul_f32_e32 v55, v55, v234
	v_mul_f32_e32 v56, v56, v234
	v_mul_f32_e32 v57, v57, v234
	v_mul_f32_e32 v58, v58, v234
	v_mul_f32_e32 v59, v59, v234
	v_mul_f32_e32 v60, v60, v234
	v_mul_f32_e32 v61, v61, v234
	v_mul_f32_e32 v62, v62, v234
	v_mul_f32_e32 v63, v63, v234
	v_mul_f32_e32 v16, v16, v234
	v_mul_f32_e32 v17, v17, v234
	v_mul_f32_e32 v18, v18, v234
	v_mul_f32_e32 v19, v19, v234
	v_mul_f32_e32 v20, v20, v234
	v_mul_f32_e32 v21, v21, v234
	v_mul_f32_e32 v22, v22, v234
	v_mul_f32_e32 v23, v23, v234
	v_mul_f32_e32 v24, v24, v234
	v_mul_f32_e32 v25, v25, v234
	v_mul_f32_e32 v26, v26, v234
	v_mul_f32_e32 v27, v27, v234
	v_mul_f32_e32 v28, v28, v234
	v_mul_f32_e32 v29, v29, v234
	v_mul_f32_e32 v30, v30, v234
	v_mul_f32_e32 v31, v31, v234
; #define MFMA32(a, b, c) __builtin_amdgcn_mfma_f32_32x32x16_bf16((a), (b), (c), 0, 0, 0)
; DI unsigned pk_bf16(float a, float b) { f32x2 v = {a, b}; bf16v2 r = __builtin_convertvector(v, bf16v2); return __builtin_bit_cast(unsigned, r); }
; template <int DK>
; DI void attn_item(const Params& p, int layer, int b, int hd, int qt, int ctxq, char* smem) {
;     ...
;             const f32x2 mref = {m_[s], m_[s]};
;             float ps = 0.f;
; #pragma unroll
;             for (int kb = 0; kb < 2; ++kb)
; #pragma unroll
;                 for (int i2 = 0; i2 < 8; ++i2) {
;                     f32x2 t = {x[kb][2 * i2], x[kb][2 * i2 + 1]};
;                     asm("v_pk_add_f32 %0, %1, %2 neg_lo:[0,1] neg_hi:[0,1]" : "=v"(t) : "v"(t), "v"(mref));
;                     const float e0 = __builtin_amdgcn_exp2f(t.x), e1 = __builtin_amdgcn_exp2f(t.y);
;                     x[kb][2 * i2] = e0; x[kb][2 * i2 + 1] = e1; ps += e0 + e1;
;                 }
;             l_[s] += ps;
; #pragma unroll
;             for (int kb = 0; kb < 2; ++kb)
; #pragma unroll
;                 for (int st = 0; st < 2; ++st) {
;                     u32x4 w;
;                     w.x = pk_bf16(x[kb][8 * st], x[kb][8 * st + 1]); w.y = pk_bf16(x[kb][8 * st + 2], x[kb][8 * st + 3]);
;                     w.z = pk_bf16(x[kb][8 * st + 4], x[kb][8 * st + 5]); w.w = pk_bf16(x[kb][8 * st + 6], x[kb][8 * st + 7]);
;                     const bf16x8 pfr = __builtin_bit_cast(bf16x8, w);
; #pragma unroll
;                     for (int d = 0; d < 2; ++d) {
;                         const bf16_t* vp = vb_ + (32 * d + r) * 68 + 32 * kb + 16 * st + 4 * h;
;                         const s16x4 lo = *(const s16x4*)vp, hi = *(const s16x4*)(vp + 8);
;                         const bf16x8 vf = __builtin_shufflevector(lo, hi, 0, 1, 2, 3, 4, 5, 6, 7);
;                         O[s][d] = MFMA32(vf, pfr, O[s][d]);
;                     }
;                 }
.Lat32_nors1f:
	v_pk_add_f32 v[80:81], v[80:81], v[146:147] neg_lo:[0,1] neg_hi:[0,1]
	v_pk_add_f32 v[82:83], v[82:83], v[146:147] neg_lo:[0,1] neg_hi:[0,1]
	v_pk_add_f32 v[84:85], v[84:85], v[146:147] neg_lo:[0,1] neg_hi:[0,1]
	v_pk_add_f32 v[86:87], v[86:87], v[146:147] neg_lo:[0,1] neg_hi:[0,1]
	v_exp_f32_e32 v80, v80
	v_exp_f32_e32 v81, v81
	v_exp_f32_e32 v82, v82
	v_exp_f32_e32 v83, v83
	v_exp_f32_e32 v84, v84
	v_exp_f32_e32 v85, v85
	v_exp_f32_e32 v86, v86
	v_exp_f32_e32 v87, v87
	v_add_f32_e32 v236, v80, v82
	v_add_f32_e32 v237, v81, v83
	v_add_f32_e32 v236, v236, v84
	v_add_f32_e32 v237, v237, v85
	v_add_f32_e32 v236, v236, v86
	v_add_f32_e32 v237, v237, v87
	v_cvt_pk_bf16_f32 v80, v80, v81
	v_cvt_pk_bf16_f32 v81, v82, v83
	v_cvt_pk_bf16_f32 v82, v84, v85
	v_cvt_pk_bf16_f32 v83, v86, v87
	v_pk_add_f32 v[88:89], v[88:89], v[146:147] neg_lo:[0,1] neg_hi:[0,1]
	v_pk_add_f32 v[90:91], v[90:91], v[146:147] neg_lo:[0,1] neg_hi:[0,1]
	v_pk_add_f32 v[92:93], v[92:93], v[146:147] neg_lo:[0,1] neg_hi:[0,1]
	v_pk_add_f32 v[94:95], v[94:95], v[146:147] neg_lo:[0,1] neg_hi:[0,1]
	v_mfma_f32_32x32x16_bf16 v[48:63], v[96:99], v[80:83], v[48:63]
	v_mfma_f32_32x32x16_bf16 v[16:31], v[112:115], v[80:83], v[16:31]
	v_exp_f32_e32 v88, v88
	v_exp_f32_e32 v89, v89
	v_exp_f32_e32 v90, v90
	v_exp_f32_e32 v91, v91
	v_exp_f32_e32 v92, v92
	v_exp_f32_e32 v93, v93
	v_exp_f32_e32 v94, v94
	v_exp_f32_e32 v95, v95
	v_add_f32_e32 v236, v236, v88
	v_add_f32_e32 v237, v237, v89
	v_add_f32_e32 v236, v236, v90
	v_add_f32_e32 v237, v237, v91
	v_add_f32_e32 v236, v236, v92
	v_add_f32_e32 v237, v237, v93
	v_add_f32_e32 v236, v236, v94
	v_add_f32_e32 v237, v237, v95
	v_cvt_pk_bf16_f32 v88, v88, v89
	v_cvt_pk_bf16_f32 v89, v90, v91
	v_cvt_pk_bf16_f32 v90, v92, v93
	v_cvt_pk_bf16_f32 v91, v94, v95
	v_pk_add_f32 v[64:65], v[64:65], v[146:147] neg_lo:[0,1] neg_hi:[0,1]
	v_pk_add_f32 v[66:67], v[66:67], v[146:147] neg_lo:[0,1] neg_hi:[0,1]
	v_pk_add_f32 v[68:69], v[68:69], v[146:147] neg_lo:[0,1] neg_hi:[0,1]
	v_pk_add_f32 v[70:71], v[70:71], v[146:147] neg_lo:[0,1] neg_hi:[0,1]
	v_mfma_f32_32x32x16_bf16 v[48:63], v[100:103], v[88:91], v[48:63]
	v_mfma_f32_32x32x16_bf16 v[16:31], v[116:119], v[88:91], v[16:31]
	s_waitcnt lgkmcnt(0)
	s_barrier
	ds_read_b128 v[128:131], v173
	ds_read_b128 v[132:135], v173 offset:4608
	ds_read_b128 v[136:139], v173 offset:32
	ds_read_b128 v[140:143], v173 offset:4640
	v_exp_f32_e32 v64, v64
	v_exp_f32_e32 v65, v65
	v_exp_f32_e32 v66, v66
	v_exp_f32_e32 v67, v67
	v_exp_f32_e32 v68, v68
	v_exp_f32_e32 v69, v69
	v_exp_f32_e32 v70, v70
	v_exp_f32_e32 v71, v71
	v_add_f32_e32 v236, v236, v64
	v_add_f32_e32 v237, v237, v65
	v_add_f32_e32 v236, v236, v66
	v_add_f32_e32 v237, v237, v67
	v_add_f32_e32 v236, v236, v68
	v_add_f32_e32 v237, v237, v69
	v_add_f32_e32 v236, v236, v70
	v_add_f32_e32 v237, v237, v71
	v_cvt_pk_bf16_f32 v64, v64, v65
	v_cvt_pk_bf16_f32 v65, v66, v67
	v_cvt_pk_bf16_f32 v66, v68, v69
	v_cvt_pk_bf16_f32 v67, v70, v71
	v_pk_add_f32 v[72:73], v[72:73], v[146:147] neg_lo:[0,1] neg_hi:[0,1]
	v_pk_add_f32 v[74:75], v[74:75], v[146:147] neg_lo:[0,1] neg_hi:[0,1]
	v_pk_add_f32 v[76:77], v[76:77], v[146:147] neg_lo:[0,1] neg_hi:[0,1]
	v_pk_add_f32 v[78:79], v[78:79], v[146:147] neg_lo:[0,1] neg_hi:[0,1]
	v_mfma_f32_32x32x16_bf16 v[48:63], v[104:107], v[64:67], v[48:63]
	v_mfma_f32_32x32x16_bf16 v[16:31], v[120:123], v[64:67], v[16:31]
	v_exp_f32_e32 v72, v72
	v_exp_f32_e32 v73, v73
	v_exp_f32_e32 v74, v74
	v_exp_f32_e32 v75, v75
	v_exp_f32_e32 v76, v76
	v_exp_f32_e32 v77, v77
	v_exp_f32_e32 v78, v78
	v_exp_f32_e32 v79, v79
	v_add_f32_e32 v236, v236, v72
	v_add_f32_e32 v237, v237, v73
	v_add_f32_e32 v236, v236, v74
	v_add_f32_e32 v237, v237, v75
	v_add_f32_e32 v236, v236, v76
	v_add_f32_e32 v237, v237, v77
	v_add_f32_e32 v236, v236, v78
	v_add_f32_e32 v237, v237, v79
	v_cvt_pk_bf16_f32 v72, v72, v73
	v_cvt_pk_bf16_f32 v73, v74, v75
	v_cvt_pk_bf16_f32 v74, v76, v77
	v_cvt_pk_bf16_f32 v75, v78, v79
	v_add_f32_e32 v236, v236, v237
	v_add_f32_e32 v170, v170, v236
	v_mfma_f32_32x32x16_bf16 v[48:63], v[108:111], v[72:75], v[48:63]
	v_mfma_f32_32x32x16_bf16 v[16:31], v[124:127], v[72:75], v[16:31]
	v_sub_f32_e32 v190, 0, v146
	v_sub_f32_e32 v191, 0, v146
	v_sub_f32_e32 v192, 0, v146
	v_sub_f32_e32 v193, 0, v146
	v_sub_f32_e32 v194, 0, v146
	v_sub_f32_e32 v195, 0, v146
	v_sub_f32_e32 v196, 0, v146
	v_sub_f32_e32 v197, 0, v146
	v_sub_f32_e32 v198, 0, v146
	v_sub_f32_e32 v199, 0, v146
	v_sub_f32_e32 v200, 0, v146
	v_sub_f32_e32 v201, 0, v146
	v_sub_f32_e32 v202, 0, v146
	v_sub_f32_e32 v203, 0, v146
	v_sub_f32_e32 v204, 0, v146
	v_sub_f32_e32 v205, 0, v146
	s_add_i32 s8, s8, 1
; #define MFMA32(a, b, c) __builtin_amdgcn_mfma_f32_32x32x16_bf16((a), (b), (c), 0, 0, 0)
; DI float shx(float v, int lane, int m) { return __int_as_float(__builtin_amdgcn_ds_bpermute((lane ^ m) << 2, __float_as_int(v))); }
; template <int DK>
; DI void attn_item(const Params& p, int layer, int b, int hd, int qt, int ctxq, char* smem) {
;     ...
;             f32x16 x[2];
; #pragma unroll
;             for (int kb = 0; kb < 2; ++kb)
; #pragma unroll
;                 for (int i = 0; i < 16; ++i) x[kb][i] = 0.f;
;             const int kofs = DK == 32 ? 32 * s : 0;
; #pragma unroll
;             for (int ks = 0; ks < NKS; ++ks) {
;                 const bf16x8 a0 = *(const bf16x8*)(kb_ + r * 72 + kofs + 16 * ks + 8 * h), a1 = *(const bf16x8*)(kb_ + (32 + r) * 72 + kofs + 16 * ks + 8 * h);
;                 const bf16x8 qv = *(const bf16x8*)(sQ + ((s * NKS + ks) * 64 + lane) * 8);
;                 x[0] = MFMA32(a0, qv, x[0]); x[1] = MFMA32(a1, qv, x[1]);
;             }
;             float mx = x[0][0];
; #pragma unroll
;             for (int i = 1; i < 16; ++i) mx = fmaxf(mx, x[0][i]);
; #pragma unroll
;             for (int i = 0; i < 16; ++i) mx = fmaxf(mx, x[1][i]);
;             mx = fmaxf(mx, shx(mx, lane, 32));
;             if (__builtin_amdgcn_ballot_w64(mx > m_[s] + 8.f) != 0) {
;                 const float mn = fmaxf(m_[s], mx);
;                 const float al = __builtin_amdgcn_exp2f(m_[s] - mn);
;                 m_[s] = mn;
;                 l_[s] *= al;
; #pragma unroll
;                 for (int d = 0; d < 2; ++d)
; #pragma unroll
;                     for (int i = 0; i < 16; ++i) O[s][d][i] *= al;
;             }
.Lat32_loop:
	s_and_b32 s9, s8, 1
	s_mul_i32 s10, s9, 0x2400
	s_mul_i32 s11, s9, 0x2200
	v_add_u32_e32 v173, s10, v149
	v_add_u32_e32 v236, s11, v172
	v_add_u32_e32 v237, 0x5800, v236
	v_add_u32_e32 v236, 0x4800, v236
	s_waitcnt lgkmcnt(0)
	v_mfma_f32_32x32x16_bf16 v[80:95], v[128:131], v[222:225], v[174:189]
	v_mfma_f32_32x32x16_bf16 v[80:95], v[136:139], v[240:243], v[80:95]
	v_mfma_f32_32x32x16_bf16 v[64:79], v[132:135], v[222:225], v[174:189]
	v_mfma_f32_32x32x16_bf16 v[64:79], v[140:143], v[240:243], v[64:79]
	ds_read2_b64 v[96:99], v236 offset0:0 offset1:2
	ds_read2_b64 v[112:115], v237 offset0:32 offset1:34
	ds_read2_b64 v[100:103], v236 offset0:4 offset1:6
	ds_read2_b64 v[116:119], v237 offset0:36 offset1:38
	ds_read2_b64 v[104:107], v236 offset0:8 offset1:10
	ds_read2_b64 v[120:123], v237 offset0:40 offset1:42
	ds_read2_b64 v[108:111], v236 offset0:12 offset1:14
	ds_read2_b64 v[124:127], v237 offset0:44 offset1:46
	ds_read_b128 v[128:131], v173 offset:64
	ds_read_b128 v[132:135], v173 offset:4672
	ds_read_b128 v[136:139], v173 offset:96
	ds_read_b128 v[140:143], v173 offset:4704
	v_max3_f32 v233, v80, v81, v82
	v_max3_f32 v233, v233, v83, v84
	v_max3_f32 v233, v233, v85, v86
	v_max3_f32 v233, v233, v87, v88
	v_max3_f32 v233, v233, v89, v90
	v_max3_f32 v233, v233, v91, v92
	v_max3_f32 v233, v233, v93, v94
	v_max3_f32 v233, v233, v95, v64
	v_max3_f32 v233, v233, v65, v66
	v_max3_f32 v233, v233, v67, v68
	v_max3_f32 v233, v233, v69, v70
	v_max3_f32 v233, v233, v71, v72
	v_max3_f32 v233, v233, v73, v74
	v_max3_f32 v233, v233, v75, v76
	v_max3_f32 v233, v233, v77, v78
	v_max_f32_e32 v233, v233, v79
	v_mov_b32_e32 v234, v233
	s_nop 1
	v_permlane32_swap_b32_e32 v234, v233
	s_nop 0
	v_max_f32_e32 v233, v233, v234
	v_cmp_lt_f32_e32 vcc, 0x41000000, v233
	s_cbranch_vccz .Lat32_nors0
	v_max_f32_e32 v239, 0, v233
	v_sub_f32_e32 v234, 0, v239
	v_exp_f32_e32 v234, v234
	v_add_f32_e32 v152, v152, v239
	v_mov_b32_e32 v153, v152
	v_mul_f32_e32 v151, v151, v234
	v_sub_f32_e32 v80, v80, v239
	v_sub_f32_e32 v81, v81, v239
	v_sub_f32_e32 v82, v82, v239
	v_sub_f32_e32 v83, v83, v239
	v_sub_f32_e32 v84, v84, v239
	v_sub_f32_e32 v85, v85, v239
	v_sub_f32_e32 v86, v86, v239
	v_sub_f32_e32 v87, v87, v239
	v_sub_f32_e32 v88, v88, v239
	v_sub_f32_e32 v89, v89, v239
	v_sub_f32_e32 v90, v90, v239
	v_sub_f32_e32 v91, v91, v239
	v_sub_f32_e32 v92, v92, v239
	v_sub_f32_e32 v93, v93, v239
	v_sub_f32_e32 v94, v94, v239
	v_sub_f32_e32 v95, v95, v239
	v_sub_f32_e32 v64, v64, v239
	v_sub_f32_e32 v65, v65, v239
	v_sub_f32_e32 v66, v66, v239
	v_sub_f32_e32 v67, v67, v239
	v_sub_f32_e32 v68, v68, v239
	v_sub_f32_e32 v69, v69, v239
	v_sub_f32_e32 v70, v70, v239
	v_sub_f32_e32 v71, v71, v239
	v_sub_f32_e32 v72, v72, v239
	v_sub_f32_e32 v73, v73, v239
	v_sub_f32_e32 v74, v74, v239
	v_sub_f32_e32 v75, v75, v239
	v_sub_f32_e32 v76, v76, v239
	v_sub_f32_e32 v77, v77, v239
	v_sub_f32_e32 v78, v78, v239
	v_sub_f32_e32 v79, v79, v239
	v_sub_f32_e32 v174, 0, v152
	v_sub_f32_e32 v175, 0, v152
	v_sub_f32_e32 v176, 0, v152
	v_sub_f32_e32 v177, 0, v152
	v_sub_f32_e32 v178, 0, v152
	v_sub_f32_e32 v179, 0, v152
	v_sub_f32_e32 v180, 0, v152
	v_sub_f32_e32 v181, 0, v152
	v_sub_f32_e32 v182, 0, v152
	v_sub_f32_e32 v183, 0, v152
	v_sub_f32_e32 v184, 0, v152
	v_sub_f32_e32 v185, 0, v152
	v_sub_f32_e32 v186, 0, v152
	v_sub_f32_e32 v187, 0, v152
	v_sub_f32_e32 v188, 0, v152
	v_sub_f32_e32 v189, 0, v152
	v_mul_f32_e32 v32, v32, v234
	v_mul_f32_e32 v33, v33, v234
	v_mul_f32_e32 v34, v34, v234
	v_mul_f32_e32 v35, v35, v234
	v_mul_f32_e32 v36, v36, v234
	v_mul_f32_e32 v37, v37, v234
	v_mul_f32_e32 v38, v38, v234
	v_mul_f32_e32 v39, v39, v234
	v_mul_f32_e32 v40, v40, v234
	v_mul_f32_e32 v41, v41, v234
	v_mul_f32_e32 v42, v42, v234
	v_mul_f32_e32 v43, v43, v234
	v_mul_f32_e32 v44, v44, v234
	v_mul_f32_e32 v45, v45, v234
	v_mul_f32_e32 v46, v46, v234
	v_mul_f32_e32 v47, v47, v234
	v_mul_f32_e32 v0, v0, v234
	v_mul_f32_e32 v1, v1, v234
	v_mul_f32_e32 v2, v2, v234
	v_mul_f32_e32 v3, v3, v234
	v_mul_f32_e32 v4, v4, v234
	v_mul_f32_e32 v5, v5, v234
	v_mul_f32_e32 v6, v6, v234
	v_mul_f32_e32 v7, v7, v234
	v_mul_f32_e32 v8, v8, v234
	v_mul_f32_e32 v9, v9, v234
	v_mul_f32_e32 v10, v10, v234
	v_mul_f32_e32 v11, v11, v234
	v_mul_f32_e32 v12, v12, v234
	v_mul_f32_e32 v13, v13, v234
	v_mul_f32_e32 v14, v14, v234
	v_mul_f32_e32 v15, v15, v234
; #define MFMA32(a, b, c) __builtin_amdgcn_mfma_f32_32x32x16_bf16((a), (b), (c), 0, 0, 0)
; DI unsigned pk_bf16(float a, float b) { f32x2 v = {a, b}; bf16v2 r = __builtin_convertvector(v, bf16v2); return __builtin_bit_cast(unsigned, r); }
; template <int DK>
; DI void attn_item(const Params& p, int layer, int b, int hd, int qt, int ctxq, char* smem) {
;     ...
;             const f32x2 mref = {m_[s], m_[s]};
;             float ps = 0.f;
; #pragma unroll
;             for (int kb = 0; kb < 2; ++kb)
; #pragma unroll
;                 for (int i2 = 0; i2 < 8; ++i2) {
;                     f32x2 t = {x[kb][2 * i2], x[kb][2 * i2 + 1]};
;                     asm("v_pk_add_f32 %0, %1, %2 neg_lo:[0,1] neg_hi:[0,1]" : "=v"(t) : "v"(t), "v"(mref));
;                     const float e0 = __builtin_amdgcn_exp2f(t.x), e1 = __builtin_amdgcn_exp2f(t.y);
;                     x[kb][2 * i2] = e0; x[kb][2 * i2 + 1] = e1; ps += e0 + e1;
;                 }
;             l_[s] += ps;
; #pragma unroll
;             for (int kb = 0; kb < 2; ++kb)
; #pragma unroll
;                 for (int st = 0; st < 2; ++st) {
;                     u32x4 w;
;                     w.x = pk_bf16(x[kb][8 * st], x[kb][8 * st + 1]); w.y = pk_bf16(x[kb][8 * st + 2], x[kb][8 * st + 3]);
;                     w.z = pk_bf16(x[kb][8 * st + 4], x[kb][8 * st + 5]); w.w = pk_bf16(x[kb][8 * st + 6], x[kb][8 * st + 7]);
;                     const bf16x8 pfr = __builtin_bit_cast(bf16x8, w);
; #pragma unroll
;                     for (int d = 0; d < 2; ++d) {
;                         const bf16_t* vp = vb_ + (32 * d + r) * 68 + 32 * kb + 16 * st + 4 * h;
;                         const s16x4 lo = *(const s16x4*)vp, hi = *(const s16x4*)(vp + 8);
;                         const bf16x8 vf = __builtin_shufflevector(lo, hi, 0, 1, 2, 3, 4, 5, 6, 7);
;                         O[s][d] = MFMA32(vf, pfr, O[s][d]);
;                     }
;                 }
;         }
;         if (kt + 1 < nkt) {
;             bf16_t* wk = sK + (cur ^ 1) * 64 * 72; bf16_t* wv = sV + (cur ^ 1) * 64 * 68;
; #pragma unroll
;             for (int i = 0; i < 2; ++i) {
;                 *(u32x4*)(wk + (srow + 32 * i) * 72 + sc8) = rk[i];
;                 *(u32x2*)(wv + (srow + 32 * i) * 68 + sc8) = (u32x2){rv[i].x, rv[i].y}; *(u32x2*)(wv + (srow + 32 * i) * 68 + sc8 + 4) = (u32x2){rv[i].z, rv[i].w};
;             }
;         }
.Lat32_nors0:
	v_exp_f32_e32 v80, v80
	v_exp_f32_e32 v81, v81
	v_exp_f32_e32 v82, v82
	v_exp_f32_e32 v83, v83
	v_exp_f32_e32 v84, v84
	v_exp_f32_e32 v85, v85
	v_exp_f32_e32 v86, v86
	v_exp_f32_e32 v87, v87
	v_add_f32_e32 v236, v80, v82
	v_add_f32_e32 v237, v81, v83
	v_add_f32_e32 v236, v236, v84
	v_add_f32_e32 v237, v237, v85
	v_add_f32_e32 v236, v236, v86
	v_add_f32_e32 v237, v237, v87
	v_cvt_pk_bf16_f32 v80, v80, v81
	v_cvt_pk_bf16_f32 v81, v82, v83
	v_cvt_pk_bf16_f32 v82, v84, v85
	v_cvt_pk_bf16_f32 v83, v86, v87
	s_waitcnt lgkmcnt(0)
	s_nop 0
	v_mfma_f32_32x32x16_bf16 v[32:47], v[96:99], v[80:83], v[32:47]
	v_mfma_f32_32x32x16_bf16 v[0:15], v[112:115], v[80:83], v[0:15]
	v_exp_f32_e32 v88, v88
	v_exp_f32_e32 v89, v89
	v_exp_f32_e32 v90, v90
	v_exp_f32_e32 v91, v91
	v_exp_f32_e32 v92, v92
	v_exp_f32_e32 v93, v93
	v_exp_f32_e32 v94, v94
	v_exp_f32_e32 v95, v95
	v_add_f32_e32 v236, v236, v88
	v_add_f32_e32 v237, v237, v89
	v_add_f32_e32 v236, v236, v90
	v_add_f32_e32 v237, v237, v91
	v_add_f32_e32 v236, v236, v92
	v_add_f32_e32 v237, v237, v93
	v_add_f32_e32 v236, v236, v94
	v_add_f32_e32 v237, v237, v95
	v_cvt_pk_bf16_f32 v88, v88, v89
	v_cvt_pk_bf16_f32 v89, v90, v91
	v_cvt_pk_bf16_f32 v90, v92, v93
	v_cvt_pk_bf16_f32 v91, v94, v95
	s_nop 1
	v_mfma_f32_32x32x16_bf16 v[32:47], v[100:103], v[88:91], v[32:47]
	v_mfma_f32_32x32x16_bf16 v[0:15], v[116:119], v[88:91], v[0:15]
	v_mfma_f32_32x32x16_bf16 v[80:95], v[128:131], v[244:247], v[190:205]
	v_mfma_f32_32x32x16_bf16 v[80:95], v[136:139], v[248:251], v[80:95]
	v_exp_f32_e32 v64, v64
	v_exp_f32_e32 v65, v65
	v_exp_f32_e32 v66, v66
	v_exp_f32_e32 v67, v67
	v_exp_f32_e32 v68, v68
	v_exp_f32_e32 v69, v69
	v_exp_f32_e32 v70, v70
	v_exp_f32_e32 v71, v71
	v_add_f32_e32 v236, v236, v64
	v_add_f32_e32 v237, v237, v65
	v_add_f32_e32 v236, v236, v66
	v_add_f32_e32 v237, v237, v67
	v_add_f32_e32 v236, v236, v68
	v_add_f32_e32 v237, v237, v69
	v_add_f32_e32 v236, v236, v70
	v_add_f32_e32 v237, v237, v71
	v_cvt_pk_bf16_f32 v64, v64, v65
	v_cvt_pk_bf16_f32 v65, v66, v67
	v_cvt_pk_bf16_f32 v66, v68, v69
	v_cvt_pk_bf16_f32 v67, v70, v71
	s_nop 1
	v_mfma_f32_32x32x16_bf16 v[32:47], v[104:107], v[64:67], v[32:47]
	v_mfma_f32_32x32x16_bf16 v[0:15], v[120:123], v[64:67], v[0:15]
	v_exp_f32_e32 v72, v72
	v_exp_f32_e32 v73, v73
	v_exp_f32_e32 v74, v74
	v_exp_f32_e32 v75, v75
	v_exp_f32_e32 v76, v76
	v_exp_f32_e32 v77, v77
	v_exp_f32_e32 v78, v78
	v_exp_f32_e32 v79, v79
	v_add_f32_e32 v236, v236, v72
	v_add_f32_e32 v237, v237, v73
	v_add_f32_e32 v236, v236, v74
	v_add_f32_e32 v237, v237, v75
	v_add_f32_e32 v236, v236, v76
	v_add_f32_e32 v237, v237, v77
	v_add_f32_e32 v236, v236, v78
	v_add_f32_e32 v237, v237, v79
	v_cvt_pk_bf16_f32 v72, v72, v73
	v_cvt_pk_bf16_f32 v73, v74, v75
	v_cvt_pk_bf16_f32 v74, v76, v77
	v_cvt_pk_bf16_f32 v75, v78, v79
	v_add_f32_e32 v236, v236, v237
	v_add_f32_e32 v151, v151, v236
	v_mfma_f32_32x32x16_bf16 v[32:47], v[108:111], v[72:75], v[32:47]
	v_mfma_f32_32x32x16_bf16 v[0:15], v[124:127], v[72:75], v[0:15]
	v_mfma_f32_32x32x16_bf16 v[64:79], v[132:135], v[244:247], v[190:205]
	v_mfma_f32_32x32x16_bf16 v[64:79], v[140:143], v[248:251], v[64:79]
	s_xor_b32 s9, s9, 1
	s_mul_i32 s10, s9, 0x2400
	s_mul_i32 s11, s9, 0x2200
	v_add_u32_e32 v233, s10, v148
	v_add_u32_e32 v234, s11, v150
	v_add_u32_e32 v239, 0x5900, v234
	v_add_u32_e32 v234, 0x4800, v234
	v_add_u32_e32 v173, s10, v149
	s_waitcnt vmcnt(0)
	ds_write_b128 v233, v[206:209]
	ds_write_b128 v233, v[210:213] offset:4608
	ds_write2_b64 v234, v[214:215], v[216:217] offset1:1
	ds_write2_b64 v239, v[218:219], v[220:221] offset1:1
	s_cmp_lt_u32 s8, 0x82
	s_cbranch_scc0 .Lat32_skipld
	s_mov_b64 s[10:11], 0x80
	v_lshl_add_u64 v[226:227], v[226:227], 0, s[10:11]
	s_mov_b64 s[10:11], 0x2000
	v_lshl_add_u64 v[230:231], v[230:231], 0, s[10:11]
	s_mov_b64 s[10:11], 0x84000
	v_lshl_add_u64 v[236:237], v[226:227], 0, s[10:11]
	global_load_dwordx4 v[206:209], v[230:231], off offset:-4096
	global_load_dwordx4 v[210:213], v[230:231], off
	global_load_dwordx4 v[214:217], v[226:227], off offset:128
	global_load_dwordx4 v[218:221], v[236:237], off offset:128
; template <int DK>
; DI void attn_item(const Params& p, int layer, int b, int hd, int qt, int ctxq, char* smem) {
;     ...
;             float mx = x[0][0];
; #pragma unroll
;             for (int i = 1; i < 16; ++i) mx = fmaxf(mx, x[0][i]);
; #pragma unroll
;             for (int i = 0; i < 16; ++i) mx = fmaxf(mx, x[1][i]);
;             mx = fmaxf(mx, shx(mx, lane, 32));
;             if (__builtin_amdgcn_ballot_w64(mx > m_[s] + 8.f) != 0) {
;                 const float mn = fmaxf(m_[s], mx);
;                 const float al = __builtin_amdgcn_exp2f(m_[s] - mn);
;                 m_[s] = mn;
;                 l_[s] *= al;
; #pragma unroll
;                 for (int d = 0; d < 2; ++d)
; #pragma unroll
;                     for (int i = 0; i < 16; ++i) O[s][d][i] *= al;
;             }
;             const f32x2 mref = {m_[s], m_[s]};
;             float ps = 0.f;
; #pragma unroll
;             for (int kb = 0; kb < 2; ++kb)
; #pragma unroll
;                 for (int i2 = 0; i2 < 8; ++i2) {
;                     f32x2 t = {x[kb][2 * i2], x[kb][2 * i2 + 1]};
;                     asm("v_pk_add_f32 %0, %1, %2 neg_lo:[0,1] neg_hi:[0,1]" : "=v"(t) : "v"(t), "v"(mref));
;                     const float e0 = __builtin_amdgcn_exp2f(t.x), e1 = __builtin_amdgcn_exp2f(t.y);
;                     x[kb][2 * i2] = e0; x[kb][2 * i2 + 1] = e1; ps += e0 + e1;
;                 }
;             l_[s] += ps;
; #pragma unroll
;             for (int kb = 0; kb < 2; ++kb)
; #pragma unroll
;                 for (int st = 0; st < 2; ++st) {
;                     u32x4 w;
;                     w.x = pk_bf16(x[kb][8 * st], x[kb][8 * st + 1]); w.y = pk_bf16(x[kb][8 * st + 2], x[kb][8 * st + 3]);
;                     w.z = pk_bf16(x[kb][8 * st + 4], x[kb][8 * st + 5]); w.w = pk_bf16(x[kb][8 * st + 6], x[kb][8 * st + 7]);
;                     const bf16x8 pfr = __builtin_bit_cast(bf16x8, w);
; #pragma unroll
;                     for (int d = 0; d < 2; ++d) {
;                         const bf16_t* vp = vb_ + (32 * d + r) * 68 + 32 * kb + 16 * st + 4 * h;
;                         const s16x4 lo = *(const s16x4*)vp, hi = *(const s16x4*)(vp + 8);
;                         const bf16x8 vf = __builtin_shufflevector(lo, hi, 0, 1, 2, 3, 4, 5, 6, 7);
;                         O[s][d] = MFMA32(vf, pfr, O[s][d]);
;                     }
;                 }
;         }
;         if (kt + 1 < nkt) {
.Lat32_skipld:
	v_max3_f32 v233, v80, v81, v82
	v_max3_f32 v233, v233, v83, v84
	v_max3_f32 v233, v233, v85, v86
	v_max3_f32 v233, v233, v87, v88
	v_max3_f32 v233, v233, v89, v90
	v_max3_f32 v233, v233, v91, v92
	v_max3_f32 v233, v233, v93, v94
	v_max3_f32 v233, v233, v95, v64
	v_max3_f32 v233, v233, v65, v66
	v_max3_f32 v233, v233, v67, v68
	v_max3_f32 v233, v233, v69, v70
	v_max3_f32 v233, v233, v71, v72
	v_max3_f32 v233, v233, v73, v74
	v_max3_f32 v233, v233, v75, v76
	v_max3_f32 v233, v233, v77, v78
	v_max_f32_e32 v233, v233, v79
	v_mov_b32_e32 v234, v233
	s_nop 1
	v_permlane32_swap_b32_e32 v234, v233
	s_nop 0
	v_max_f32_e32 v233, v233, v234
	v_cmp_lt_f32_e32 vcc, 0x41000000, v233
	s_cbranch_vccz .Lat32_nors1
	v_max_f32_e32 v239, 0, v233
	v_sub_f32_e32 v234, 0, v239
	v_exp_f32_e32 v234, v234
	v_add_f32_e32 v146, v146, v239
	v_mov_b32_e32 v147, v146
	v_mul_f32_e32 v170, v170, v234
	v_sub_f32_e32 v80, v80, v239
	v_sub_f32_e32 v81, v81, v239
	v_sub_f32_e32 v82, v82, v239
	v_sub_f32_e32 v83, v83, v239
	v_sub_f32_e32 v84, v84, v239
	v_sub_f32_e32 v85, v85, v239
	v_sub_f32_e32 v86, v86, v239
	v_sub_f32_e32 v87, v87, v239
	v_sub_f32_e32 v88, v88, v239
	v_sub_f32_e32 v89, v89, v239
	v_sub_f32_e32 v90, v90, v239
	v_sub_f32_e32 v91, v91, v239
	v_sub_f32_e32 v92, v92, v239
	v_sub_f32_e32 v93, v93, v239
	v_sub_f32_e32 v94, v94, v239
	v_sub_f32_e32 v95, v95, v239
	v_sub_f32_e32 v64, v64, v239
	v_sub_f32_e32 v65, v65, v239
	v_sub_f32_e32 v66, v66, v239
	v_sub_f32_e32 v67, v67, v239
	v_sub_f32_e32 v68, v68, v239
	v_sub_f32_e32 v69, v69, v239
	v_sub_f32_e32 v70, v70, v239
	v_sub_f32_e32 v71, v71, v239
	v_sub_f32_e32 v72, v72, v239
	v_sub_f32_e32 v73, v73, v239
	v_sub_f32_e32 v74, v74, v239
	v_sub_f32_e32 v75, v75, v239
	v_sub_f32_e32 v76, v76, v239
	v_sub_f32_e32 v77, v77, v239
	v_sub_f32_e32 v78, v78, v239
	v_sub_f32_e32 v79, v79, v239
	v_sub_f32_e32 v190, 0, v146
	v_sub_f32_e32 v191, 0, v146
	v_sub_f32_e32 v192, 0, v146
	v_sub_f32_e32 v193, 0, v146
	v_sub_f32_e32 v194, 0, v146
	v_sub_f32_e32 v195, 0, v146
	v_sub_f32_e32 v196, 0, v146
	v_sub_f32_e32 v197, 0, v146
	v_sub_f32_e32 v198, 0, v146
	v_sub_f32_e32 v199, 0, v146
	v_sub_f32_e32 v200, 0, v146
	v_sub_f32_e32 v201, 0, v146
	v_sub_f32_e32 v202, 0, v146
	v_sub_f32_e32 v203, 0, v146
	v_sub_f32_e32 v204, 0, v146
	v_sub_f32_e32 v205, 0, v146
	v_mul_f32_e32 v48, v48, v234
	v_mul_f32_e32 v49, v49, v234
	v_mul_f32_e32 v50, v50, v234
	v_mul_f32_e32 v51, v51, v234
	v_mul_f32_e32 v52, v52, v234
	v_mul_f32_e32 v53, v53, v234
	v_mul_f32_e32 v54, v54, v234
	v_mul_f32_e32 v55, v55, v234
	v_mul_f32_e32 v56, v56, v234
	v_mul_f32_e32 v57, v57, v234
	v_mul_f32_e32 v58, v58, v234
	v_mul_f32_e32 v59, v59, v234
	v_mul_f32_e32 v60, v60, v234
	v_mul_f32_e32 v61, v61, v234
	v_mul_f32_e32 v62, v62, v234
	v_mul_f32_e32 v63, v63, v234
	v_mul_f32_e32 v16, v16, v234
	v_mul_f32_e32 v17, v17, v234
	v_mul_f32_e32 v18, v18, v234
	v_mul_f32_e32 v19, v19, v234
	v_mul_f32_e32 v20, v20, v234
	v_mul_f32_e32 v21, v21, v234
	v_mul_f32_e32 v22, v22, v234
	v_mul_f32_e32 v23, v23, v234
	v_mul_f32_e32 v24, v24, v234
	v_mul_f32_e32 v25, v25, v234
	v_mul_f32_e32 v26, v26, v234
	v_mul_f32_e32 v27, v27, v234
	v_mul_f32_e32 v28, v28, v234
	v_mul_f32_e32 v29, v29, v234
	v_mul_f32_e32 v30, v30, v234
	v_mul_f32_e32 v31, v31, v234
.Lat32_nors1:
	v_exp_f32_e32 v80, v80
	v_exp_f32_e32 v81, v81
	v_exp_f32_e32 v82, v82
	v_exp_f32_e32 v83, v83
	v_exp_f32_e32 v84, v84
	v_exp_f32_e32 v85, v85
	v_exp_f32_e32 v86, v86
	v_exp_f32_e32 v87, v87
	v_add_f32_e32 v236, v80, v82
	v_add_f32_e32 v237, v81, v83
	v_add_f32_e32 v236, v236, v84
	v_add_f32_e32 v237, v237, v85
	v_add_f32_e32 v236, v236, v86
	v_add_f32_e32 v237, v237, v87
	v_cvt_pk_bf16_f32 v80, v80, v81
	v_cvt_pk_bf16_f32 v81, v82, v83
	v_cvt_pk_bf16_f32 v82, v84, v85
	v_cvt_pk_bf16_f32 v83, v86, v87
	s_nop 1
	v_mfma_f32_32x32x16_bf16 v[48:63], v[96:99], v[80:83], v[48:63]
	v_mfma_f32_32x32x16_bf16 v[16:31], v[112:115], v[80:83], v[16:31]
	v_exp_f32_e32 v88, v88
	v_exp_f32_e32 v89, v89
	v_exp_f32_e32 v90, v90
	v_exp_f32_e32 v91, v91
	v_exp_f32_e32 v92, v92
	v_exp_f32_e32 v93, v93
	v_exp_f32_e32 v94, v94
	v_exp_f32_e32 v95, v95
	v_add_f32_e32 v236, v236, v88
	v_add_f32_e32 v237, v237, v89
	v_add_f32_e32 v236, v236, v90
	v_add_f32_e32 v237, v237, v91
	v_add_f32_e32 v236, v236, v92
	v_add_f32_e32 v237, v237, v93
	v_add_f32_e32 v236, v236, v94
	v_add_f32_e32 v237, v237, v95
	v_cvt_pk_bf16_f32 v88, v88, v89
	v_cvt_pk_bf16_f32 v89, v90, v91
	v_cvt_pk_bf16_f32 v90, v92, v93
	v_cvt_pk_bf16_f32 v91, v94, v95
	s_nop 1
	v_mfma_f32_32x32x16_bf16 v[48:63], v[100:103], v[88:91], v[48:63]
	v_mfma_f32_32x32x16_bf16 v[16:31], v[116:119], v[88:91], v[16:31]
	s_waitcnt lgkmcnt(0)
	s_barrier
	ds_read_b128 v[128:131], v173
	ds_read_b128 v[132:135], v173 offset:4608
	ds_read_b128 v[136:139], v173 offset:32
	ds_read_b128 v[140:143], v173 offset:4640
	v_exp_f32_e32 v64, v64
	v_exp_f32_e32 v65, v65
	v_exp_f32_e32 v66, v66
	v_exp_f32_e32 v67, v67
	v_exp_f32_e32 v68, v68
	v_exp_f32_e32 v69, v69
	v_exp_f32_e32 v70, v70
	v_exp_f32_e32 v71, v71
	v_add_f32_e32 v236, v236, v64
	v_add_f32_e32 v237, v237, v65
	v_add_f32_e32 v236, v236, v66
	v_add_f32_e32 v237, v237, v67
	v_add_f32_e32 v236, v236, v68
	v_add_f32_e32 v237, v237, v69
	v_add_f32_e32 v236, v236, v70
	v_add_f32_e32 v237, v237, v71
	v_cvt_pk_bf16_f32 v64, v64, v65
	v_cvt_pk_bf16_f32 v65, v66, v67
	v_cvt_pk_bf16_f32 v66, v68, v69
	v_cvt_pk_bf16_f32 v67, v70, v71
	s_nop 1
	v_mfma_f32_32x32x16_bf16 v[48:63], v[104:107], v[64:67], v[48:63]
	v_mfma_f32_32x32x16_bf16 v[16:31], v[120:123], v[64:67], v[16:31]
	v_exp_f32_e32 v72, v72
	v_exp_f32_e32 v73, v73
	v_exp_f32_e32 v74, v74
	v_exp_f32_e32 v75, v75
	v_exp_f32_e32 v76, v76
	v_exp_f32_e32 v77, v77
	v_exp_f32_e32 v78, v78
	v_exp_f32_e32 v79, v79
	v_add_f32_e32 v236, v236, v72
	v_add_f32_e32 v237, v237, v73
	v_add_f32_e32 v236, v236, v74
	v_add_f32_e32 v237, v237, v75
	v_add_f32_e32 v236, v236, v76
	v_add_f32_e32 v237, v237, v77
	v_add_f32_e32 v236, v236, v78
	v_add_f32_e32 v237, v237, v79
	v_cvt_pk_bf16_f32 v72, v72, v73
	v_cvt_pk_bf16_f32 v73, v74, v75
	v_cvt_pk_bf16_f32 v74, v76, v77
	v_cvt_pk_bf16_f32 v75, v78, v79
	v_add_f32_e32 v236, v236, v237
	v_add_f32_e32 v170, v170, v236
	v_mfma_f32_32x32x16_bf16 v[48:63], v[108:111], v[72:75], v[48:63]
	v_mfma_f32_32x32x16_bf16 v[16:31], v[124:127], v[72:75], v[16:31]
	s_add_i32 s8, s8, 1
	s_cmpk_eq_i32 s8, 0x83
	s_cbranch_scc0 .Lat32_loop
	s_waitcnt lgkmcnt(0)
